# v24: v23 + P2 memory-k/v rows handled by high waves (1792..2047) instead of the already longest low waves
# speedup vs baseline: 1.0006x; 1.0006x over previous
; __device__ __forceinline__ u32x4 pack8(const float* f) { u32x4 o; o.x = pk2(f[0], f[1]); o.y = pk2(f[2], f[3]); o.z = pk2(f[4], f[5]); o.w = pk2(f[6], f[7]); return o; }
; __global__ void __launch_bounds__(512, 2) mega_fwd(Args args) {
;     ...
;         for (int row = gw; row < NMEM; row += NGW) {
;             const float* kp = MEMKV + (size_t)row * 1024 + lane * 8; const f32x4 a = *(const f32x4*)kp, b = *(const f32x4*)(kp + 4);
;             float f[8] = {a.x, a.y, a.z, a.w, b.x, b.y, b.z, b.w}; float ss = 0.f;
; #pragma unroll
;             for (int e = 0; e < 8; ++e) ss += f[e] * f[e];
;             ss += __shfl_xor(ss, 1); ss += __shfl_xor(ss, 2); ss += __shfl_xor(ss, 4); ss += __shfl_xor(ss, 8);
;             const float rstd = rsqrtf(ss * (1.f / HD) + EPS);
; #pragma unroll
;             for (int e = 0; e < 8; ++e) f[e] = f[e] * rstd * mem_k_norm[(lane & 15) * 8 + e];
;             float* ko = out + O_PMK + (size_t)row * 512 + lane * 8; *(f32x4*)ko = (f32x4){f[0], f[1], f[2], f[3]}; *(f32x4*)(ko + 4) = (f32x4){f[4], f[5], f[6], f[7]};
;             *(u32x4*)(MK + (size_t)row * 512 + lane * 8) = pack8(f);
;             const float* vp = kp + 512; const f32x4 c = *(const f32x4*)vp, dd = *(const f32x4*)(vp + 4);
;             float* vo = out + O_PMV + (size_t)row * 512 + lane * 8; *(f32x4*)vo = c; *(f32x4*)(vo + 4) = dd;
;             float fv[8] = {c.x, c.y, c.z, c.w, dd.x, dd.y, dd.z, dd.w}; *(u32x4*)(MV + (size_t)row * 512 + lane * 8) = pack8(fv);
;         }
.LBB0_333:
	s_or_b64 exec, exec, s[6:7]
	s_cmpk_gt_i32 s12, 0x6ff
	s_cbranch_scc0 .LBB0_336
	s_sub_i32 s100, s12, 0x700
	s_ashr_i32 s101, s100, 31
	v_mbcnt_lo_u32_b32 v0, -1, 0
	v_mbcnt_hi_u32_b32 v0, -1, v0
	v_and_b32_e32 v2, 64, v0
	v_xor_b32_e32 v1, 1, v0
	v_add_u32_e32 v2, 64, v2
	v_cmp_lt_i32_e32 vcc, v1, v2
	s_load_dwordx4 s[20:23], s[8:9], 0xf0
	s_load_dwordx2 s[4:5], s[8:9], 0xb0
	v_cndmask_b32_e32 v1, v0, v1, vcc
	v_lshlrev_b32_e32 v4, 2, v1
	v_xor_b32_e32 v1, 2, v0
	v_cmp_lt_i32_e32 vcc, v1, v2
	v_mov_b32_e32 v93, 0
	s_ashr_i32 s13, s12, 31
	v_cndmask_b32_e32 v1, v0, v1, vcc
	v_lshlrev_b32_e32 v5, 2, v1
	v_xor_b32_e32 v1, 4, v0
	v_cmp_lt_i32_e32 vcc, v1, v2
	v_mov_b32_e32 v8, 0x358637bd
	s_mov_b32 s27, 0xfffc0000
	v_cndmask_b32_e32 v1, v0, v1, vcc
	v_lshlrev_b32_e32 v6, 2, v1
	v_xor_b32_e32 v1, 8, v0
	v_cmp_lt_i32_e32 vcc, v1, v2
	s_mov_b32 s28, 0x918f000
	s_mov_b32 s29, s100
	v_cndmask_b32_e32 v0, v0, v1, vcc
	v_lshlrev_b32_e32 v7, 2, v0
	s_waitcnt lgkmcnt(0)
	v_lshl_add_u64 v[0:1], s[4:5], 0, v[92:93]
	s_lshl_b64 s[4:5], s[100:101], 10
	s_add_u32 s4, s22, s4
	v_lshlrev_b32_e32 v92, 4, v192
	s_addc_u32 s5, s23, s5
	v_lshl_add_u64 v[2:3], s[4:5], 0, v[92:93]
	s_mov_b64 s[4:5], 0x63c0000
	s_ashr_i32 s15, s14, 31
	v_lshl_add_u64 v[2:3], v[2:3], 0, s[4:5]
	s_lshl_b64 s[4:5], s[14:15], 10
	s_lshl_b64 s[6:7], s[100:101], 11
	s_add_u32 s6, s20, s6
	s_addc_u32 s7, s21, s7
	s_lshl_b64 s[8:9], s[14:15], 11
	s_lshl_b64 s[10:11], s[100:101], 12
	s_add_u32 s10, s22, s10
	v_lshlrev_b32_e32 v92, 5, v192
	s_addc_u32 s11, s23, s11
	s_lshl_b64 s[18:19], s[14:15], 12
	s_mov_b64 s[20:21], 0x6500000
	s_mov_b32 s13, 0x800000
	s_mov_b32 s15, 0x910f000
	s_mov_b64 s[22:23], 0x6500800
